# attention fast path v3: softmax exp/sum/cvt done per 8-key quarter, each quarter hidden in the gaps of the previous quarter's 4 PV MFMAs
# baseline (speedup 1.0000x reference)
.LaF1_2:
	v_sub_f32_e32 v66, v66, v183
	v_sub_f32_e32 v67, v67, v183
	v_sub_f32_e32 v68, v68, v183
	v_sub_f32_e32 v69, v69, v183
	v_sub_f32_e32 v70, v70, v183
	v_sub_f32_e32 v71, v71, v183
	v_sub_f32_e32 v72, v72, v183
	v_sub_f32_e32 v73, v73, v183
	v_exp_f32_e32 v66, v66
	v_exp_f32_e32 v67, v67
	v_exp_f32_e32 v68, v68
	v_exp_f32_e32 v69, v69
	v_exp_f32_e32 v70, v70
	v_exp_f32_e32 v71, v71
	v_exp_f32_e32 v72, v72
	v_exp_f32_e32 v73, v73
	v_pk_add_f32 v[184:185], v[66:67], v[70:71]
	v_pk_add_f32 v[186:187], v[68:69], v[72:73]
	v_cvt_pk_bf16_f32 v66, v66, v67
	v_cvt_pk_bf16_f32 v67, v68, v69
	v_cvt_pk_bf16_f32 v68, v70, v71
	v_cvt_pk_bf16_f32 v69, v72, v73
	s_setprio 1
	s_nop 1
	s_waitcnt lgkmcnt(5)
	v_mfma_f32_32x32x16_bf16 v[50:65], v[196:199], v[66:69], v[50:65]
	ds_read_b128 v[220:223], v252 offset:34848
	v_sub_f32_e32 v74, v74, v183
	v_sub_f32_e32 v75, v75, v183
	v_sub_f32_e32 v76, v76, v183
	v_sub_f32_e32 v77, v77, v183
	v_sub_f32_e32 v78, v78, v183
	v_sub_f32_e32 v79, v79, v183
	s_waitcnt lgkmcnt(5)
	v_mfma_f32_32x32x16_bf16 v[34:49], v[200:203], v[66:69], v[34:49]
	ds_read_b128 v[224:227], v252 offset:39456
	v_sub_f32_e32 v80, v80, v183
	v_sub_f32_e32 v81, v81, v183
	v_exp_f32_e32 v74, v74
	v_exp_f32_e32 v75, v75
	v_exp_f32_e32 v76, v76
	v_exp_f32_e32 v77, v77
	s_waitcnt lgkmcnt(5)
	v_mfma_f32_32x32x16_bf16 v[18:33], v[204:207], v[66:69], v[18:33]
	ds_read_b128 v[228:231], v252 offset:25664
	v_exp_f32_e32 v78, v78
	v_exp_f32_e32 v79, v79
	v_exp_f32_e32 v80, v80
	v_exp_f32_e32 v81, v81
	v_pk_add_f32 v[184:185], v[184:185], v[74:75]
	v_pk_add_f32 v[186:187], v[186:187], v[76:77]
	s_waitcnt lgkmcnt(5)
	v_mfma_f32_32x32x16_bf16 v[2:17], v[208:211], v[66:69], v[2:17]
	ds_read_b128 v[232:235], v252 offset:30272
	v_pk_add_f32 v[184:185], v[184:185], v[78:79]
	v_pk_add_f32 v[186:187], v[186:187], v[80:81]
	v_cvt_pk_bf16_f32 v70, v74, v75
	v_cvt_pk_bf16_f32 v71, v76, v77
	v_cvt_pk_bf16_f32 v72, v78, v79
	v_cvt_pk_bf16_f32 v73, v80, v81
	s_nop 1
	s_waitcnt lgkmcnt(5)
	v_mfma_f32_32x32x16_bf16 v[50:65], v[212:215], v[70:73], v[50:65]
	ds_read_b128 v[236:239], v252 offset:34880
	v_sub_f32_e32 v82, v82, v183
	v_sub_f32_e32 v83, v83, v183
	v_sub_f32_e32 v84, v84, v183
	v_sub_f32_e32 v85, v85, v183
	v_sub_f32_e32 v86, v86, v183
	v_sub_f32_e32 v87, v87, v183
	s_waitcnt lgkmcnt(5)
	v_mfma_f32_32x32x16_bf16 v[34:49], v[216:219], v[70:73], v[34:49]
	ds_read_b128 v[240:243], v252 offset:39488
	v_sub_f32_e32 v88, v88, v183
	v_sub_f32_e32 v89, v89, v183
	v_exp_f32_e32 v82, v82
	v_exp_f32_e32 v83, v83
	v_exp_f32_e32 v84, v84
	v_exp_f32_e32 v85, v85
	s_waitcnt lgkmcnt(5)
	v_mfma_f32_32x32x16_bf16 v[18:33], v[220:223], v[70:73], v[18:33]
	ds_read_b128 v[196:199], v252 offset:25696
	v_exp_f32_e32 v86, v86
	v_exp_f32_e32 v87, v87
	v_exp_f32_e32 v88, v88
	v_exp_f32_e32 v89, v89
	v_pk_add_f32 v[184:185], v[184:185], v[82:83]
	v_pk_add_f32 v[186:187], v[186:187], v[84:85]
	s_waitcnt lgkmcnt(5)
	v_mfma_f32_32x32x16_bf16 v[2:17], v[224:227], v[70:73], v[2:17]
	ds_read_b128 v[200:203], v252 offset:30304
	v_pk_add_f32 v[184:185], v[184:185], v[86:87]
	v_pk_add_f32 v[186:187], v[186:187], v[88:89]
	v_cvt_pk_bf16_f32 v74, v82, v83
	v_cvt_pk_bf16_f32 v75, v84, v85
	v_cvt_pk_bf16_f32 v76, v86, v87
	v_cvt_pk_bf16_f32 v77, v88, v89
	s_nop 1
	s_waitcnt lgkmcnt(5)
	v_mfma_f32_32x32x16_bf16 v[50:65], v[228:231], v[74:77], v[50:65]
	ds_read_b128 v[204:207], v252 offset:34912
	v_sub_f32_e32 v90, v90, v183
	v_sub_f32_e32 v91, v91, v183
	v_sub_f32_e32 v92, v92, v183
	v_sub_f32_e32 v93, v93, v183
	v_sub_f32_e32 v94, v94, v183
	v_sub_f32_e32 v95, v95, v183
	v_sub_f32_e32 v96, v96, v183
	s_waitcnt lgkmcnt(5)
	v_mfma_f32_32x32x16_bf16 v[34:49], v[232:235], v[74:77], v[34:49]
	ds_read_b128 v[208:211], v252 offset:39520
	v_sub_f32_e32 v97, v97, v183
	v_exp_f32_e32 v90, v90
	v_exp_f32_e32 v91, v91
	v_exp_f32_e32 v92, v92
	v_exp_f32_e32 v93, v93
	v_exp_f32_e32 v94, v94
	v_exp_f32_e32 v95, v95
	s_waitcnt lgkmcnt(5)
	v_mfma_f32_32x32x16_bf16 v[18:33], v[236:239], v[74:77], v[18:33]
	v_exp_f32_e32 v96, v96
	v_exp_f32_e32 v97, v97
	v_pk_add_f32 v[184:185], v[184:185], v[90:91]
	v_pk_add_f32 v[186:187], v[186:187], v[92:93]
	v_pk_add_f32 v[184:185], v[184:185], v[94:95]
	v_pk_add_f32 v[186:187], v[186:187], v[96:97]
	v_cvt_pk_bf16_f32 v78, v90, v91
	s_waitcnt lgkmcnt(4)
	v_mfma_f32_32x32x16_bf16 v[2:17], v[240:243], v[74:77], v[2:17]
	v_cvt_pk_bf16_f32 v79, v92, v93
	v_cvt_pk_bf16_f32 v80, v94, v95
	v_cvt_pk_bf16_f32 v81, v96, v97
	v_pk_add_f32 v[184:185], v[184:185], v[186:187]
	v_add_f32_e32 v184, v184, v185
	v_add_f32_e32 v182, v182, v184
	s_nop 1
	s_waitcnt lgkmcnt(3)
	v_mfma_f32_32x32x16_bf16 v[50:65], v[196:199], v[78:81], v[50:65]
	s_bitcmp1_b32 s51, 0
	s_cselect_b32 s99, 0xac00, 0
	s_add_i32 s99, s99, 0
	v_add_u32_e32 v250, s99, v170
	s_waitcnt lgkmcnt(2)
	v_mfma_f32_32x32x16_bf16 v[34:49], v[200:203], v[78:81], v[34:49]
	s_waitcnt vmcnt(4)
	ds_write_b128 v250, v[98:101]
	s_waitcnt vmcnt(3)
	ds_write_b128 v250, v[102:105] offset:12800
	s_waitcnt lgkmcnt(3)
	v_mfma_f32_32x32x16_bf16 v[18:33], v[204:207], v[78:81], v[18:33]
	v_add_u32_e32 v250, s99, v172
	s_waitcnt vmcnt(2)
	ds_write_b128 v250, v[106:109] offset:256
	v_add_u32_e32 v250, s99, v169
	s_waitcnt lgkmcnt(3)
	v_mfma_f32_32x32x16_bf16 v[2:17], v[208:211], v[78:81], v[2:17]
	s_waitcnt vmcnt(1)
	ds_write_b128 v250, v[114:117] offset:25600
	s_waitcnt vmcnt(0)
	ds_write_b128 v250, v[146:149] offset:34816
	s_setprio 0
	s_branch .LBB0_1478

.LaF2_2:
	v_sub_f32_e32 v66, v66, v183
	v_sub_f32_e32 v67, v67, v183
	v_sub_f32_e32 v68, v68, v183
	v_sub_f32_e32 v69, v69, v183
	v_sub_f32_e32 v70, v70, v183
	v_sub_f32_e32 v71, v71, v183
	v_sub_f32_e32 v72, v72, v183
	v_sub_f32_e32 v73, v73, v183
	v_exp_f32_e32 v66, v66
	v_exp_f32_e32 v67, v67
	v_exp_f32_e32 v68, v68
	v_exp_f32_e32 v69, v69
	v_exp_f32_e32 v70, v70
	v_exp_f32_e32 v71, v71
	v_exp_f32_e32 v72, v72
	v_exp_f32_e32 v73, v73
	v_pk_add_f32 v[184:185], v[66:67], v[70:71]
	v_pk_add_f32 v[186:187], v[68:69], v[72:73]
	v_cvt_pk_bf16_f32 v66, v66, v67
	v_cvt_pk_bf16_f32 v67, v68, v69
	v_cvt_pk_bf16_f32 v68, v70, v71
	v_cvt_pk_bf16_f32 v69, v72, v73
	s_setprio 1
	s_nop 1
	s_waitcnt lgkmcnt(5)
	v_mfma_f32_32x32x16_bf16 v[50:65], v[196:199], v[66:69], v[50:65]
	ds_read_b128 v[220:223], v252 offset:34848
	v_sub_f32_e32 v74, v74, v183
	v_sub_f32_e32 v75, v75, v183
	v_sub_f32_e32 v76, v76, v183
	v_sub_f32_e32 v77, v77, v183
	v_sub_f32_e32 v78, v78, v183
	v_sub_f32_e32 v79, v79, v183
	s_waitcnt lgkmcnt(5)
	v_mfma_f32_32x32x16_bf16 v[34:49], v[200:203], v[66:69], v[34:49]
	ds_read_b128 v[224:227], v252 offset:39456
	v_sub_f32_e32 v80, v80, v183
	v_sub_f32_e32 v81, v81, v183
	v_exp_f32_e32 v74, v74
	v_exp_f32_e32 v75, v75
	v_exp_f32_e32 v76, v76
	v_exp_f32_e32 v77, v77
	s_waitcnt lgkmcnt(5)
	v_mfma_f32_32x32x16_bf16 v[18:33], v[204:207], v[66:69], v[18:33]
	ds_read_b128 v[228:231], v252 offset:25664
	v_exp_f32_e32 v78, v78
	v_exp_f32_e32 v79, v79
	v_exp_f32_e32 v80, v80
	v_exp_f32_e32 v81, v81
	v_pk_add_f32 v[184:185], v[184:185], v[74:75]
	v_pk_add_f32 v[186:187], v[186:187], v[76:77]
	s_waitcnt lgkmcnt(5)
	v_mfma_f32_32x32x16_bf16 v[2:17], v[208:211], v[66:69], v[2:17]
	ds_read_b128 v[232:235], v252 offset:30272
	v_pk_add_f32 v[184:185], v[184:185], v[78:79]
	v_pk_add_f32 v[186:187], v[186:187], v[80:81]
	v_cvt_pk_bf16_f32 v70, v74, v75
	v_cvt_pk_bf16_f32 v71, v76, v77
	v_cvt_pk_bf16_f32 v72, v78, v79
	v_cvt_pk_bf16_f32 v73, v80, v81
	s_nop 1
	s_waitcnt lgkmcnt(5)
	v_mfma_f32_32x32x16_bf16 v[50:65], v[212:215], v[70:73], v[50:65]
	ds_read_b128 v[236:239], v252 offset:34880
	v_sub_f32_e32 v82, v82, v183
	v_sub_f32_e32 v83, v83, v183
	v_sub_f32_e32 v84, v84, v183
	v_sub_f32_e32 v85, v85, v183
	v_sub_f32_e32 v86, v86, v183
	v_sub_f32_e32 v87, v87, v183
	s_waitcnt lgkmcnt(5)
	v_mfma_f32_32x32x16_bf16 v[34:49], v[216:219], v[70:73], v[34:49]
	ds_read_b128 v[240:243], v252 offset:39488
	v_sub_f32_e32 v88, v88, v183
	v_sub_f32_e32 v89, v89, v183
	v_exp_f32_e32 v82, v82
	v_exp_f32_e32 v83, v83
	v_exp_f32_e32 v84, v84
	v_exp_f32_e32 v85, v85
	s_waitcnt lgkmcnt(5)
	v_mfma_f32_32x32x16_bf16 v[18:33], v[220:223], v[70:73], v[18:33]
	ds_read_b128 v[196:199], v252 offset:25696
	v_exp_f32_e32 v86, v86
	v_exp_f32_e32 v87, v87
	v_exp_f32_e32 v88, v88
	v_exp_f32_e32 v89, v89
	v_pk_add_f32 v[184:185], v[184:185], v[82:83]
	v_pk_add_f32 v[186:187], v[186:187], v[84:85]
	s_waitcnt lgkmcnt(5)
	v_mfma_f32_32x32x16_bf16 v[2:17], v[224:227], v[70:73], v[2:17]
	ds_read_b128 v[200:203], v252 offset:30304
	v_pk_add_f32 v[184:185], v[184:185], v[86:87]
	v_pk_add_f32 v[186:187], v[186:187], v[88:89]
	v_cvt_pk_bf16_f32 v74, v82, v83
	v_cvt_pk_bf16_f32 v75, v84, v85
	v_cvt_pk_bf16_f32 v76, v86, v87
	v_cvt_pk_bf16_f32 v77, v88, v89
	s_nop 1
	s_waitcnt lgkmcnt(5)
	v_mfma_f32_32x32x16_bf16 v[50:65], v[228:231], v[74:77], v[50:65]
	ds_read_b128 v[204:207], v252 offset:34912
	v_sub_f32_e32 v90, v90, v183
	v_sub_f32_e32 v91, v91, v183
	v_sub_f32_e32 v92, v92, v183
	v_sub_f32_e32 v93, v93, v183
	v_sub_f32_e32 v94, v94, v183
	v_sub_f32_e32 v95, v95, v183
	v_sub_f32_e32 v96, v96, v183
	s_waitcnt lgkmcnt(5)
	v_mfma_f32_32x32x16_bf16 v[34:49], v[232:235], v[74:77], v[34:49]
	ds_read_b128 v[208:211], v252 offset:39520
	v_sub_f32_e32 v97, v97, v183
	v_exp_f32_e32 v90, v90
	v_exp_f32_e32 v91, v91
	v_exp_f32_e32 v92, v92
	v_exp_f32_e32 v93, v93
	v_exp_f32_e32 v94, v94
	v_exp_f32_e32 v95, v95
	s_waitcnt lgkmcnt(5)
	v_mfma_f32_32x32x16_bf16 v[18:33], v[236:239], v[74:77], v[18:33]
	v_exp_f32_e32 v96, v96
	v_exp_f32_e32 v97, v97
	v_pk_add_f32 v[184:185], v[184:185], v[90:91]
	v_pk_add_f32 v[186:187], v[186:187], v[92:93]
	v_pk_add_f32 v[184:185], v[184:185], v[94:95]
	v_pk_add_f32 v[186:187], v[186:187], v[96:97]
	v_cvt_pk_bf16_f32 v78, v90, v91
	s_waitcnt lgkmcnt(4)
	v_mfma_f32_32x32x16_bf16 v[2:17], v[240:243], v[74:77], v[2:17]
	v_cvt_pk_bf16_f32 v79, v92, v93
	v_cvt_pk_bf16_f32 v80, v94, v95
	v_cvt_pk_bf16_f32 v81, v96, v97
	v_pk_add_f32 v[184:185], v[184:185], v[186:187]
	v_add_f32_e32 v184, v184, v185
	v_add_f32_e32 v182, v182, v184
	s_nop 1
	s_waitcnt lgkmcnt(3)
	v_mfma_f32_32x32x16_bf16 v[50:65], v[196:199], v[78:81], v[50:65]
	s_bitcmp1_b32 s36, 0
	s_cselect_b32 s99, 0xac00, 0
	s_add_i32 s99, s99, 0
	v_add_u32_e32 v250, s99, v170
	s_waitcnt lgkmcnt(2)
	v_mfma_f32_32x32x16_bf16 v[34:49], v[200:203], v[78:81], v[34:49]
	s_waitcnt vmcnt(4)
	ds_write_b128 v250, v[98:101]
	s_waitcnt vmcnt(3)
	ds_write_b128 v250, v[102:105] offset:12800
	s_waitcnt lgkmcnt(3)
	v_mfma_f32_32x32x16_bf16 v[18:33], v[204:207], v[78:81], v[18:33]
	v_add_u32_e32 v250, s99, v172
	s_waitcnt vmcnt(2)
	ds_write_b128 v250, v[106:109] offset:256
	v_add_u32_e32 v250, s99, v169
	s_waitcnt lgkmcnt(3)
	v_mfma_f32_32x32x16_bf16 v[2:17], v[208:211], v[78:81], v[2:17]
	s_waitcnt vmcnt(1)
	ds_write_b128 v250, v[126:129] offset:25600
	s_waitcnt vmcnt(0)
	ds_write_b128 v250, v[150:153] offset:34816
	s_setprio 0
	s_branch .LBB0_1490
